# P1 and P5 sample-row mini GEMMs: all 16 operand fragments of a wave requested up front (same change as the P8 one)
# speedup vs baseline: 1.0113x; 1.0054x over previous
; __device__ __forceinline__ unsigned f2bf(float f) { unsigned u = __float_as_uint(f); return (u + 0x7fffu + ((u >> 16) & 1u)) >> 16; }
; template <int MODE>
; __device__ __forceinline__ void mini_gemm(LAS unsigned char* lds, const bf16_t* A, const bf16_t* Bt, int K, int N, bf16_t* O, int ldc, const float* rstd, float* sumsq, int bx, int G, int tid, int wave, int lane) {
;     ...
;     for (int tile = bx; tile < ntiles; tile += G) {
;         const int m0 = (tile / ntn) * 32, n0 = (tile % ntn) * 32;
;         const bf16_t* ap = A + (size_t)(m0 + r) * K + wave * kw + 8 * hf; const bf16_t* bp = Bt + (size_t)(n0 + r) * K + wave * kw + 8 * hf;
;         f32x16 acc; for (int i = 0; i < 16; ++i) acc[i] = 0.f;
;         for (int k = 0; k < kw; k += 16) { const bf16x8 af = *(const bf16x8*)(ap + k), bf = *(const bf16x8*)(bp + k); acc = __builtin_amdgcn_mfma_f32_32x32x16_bf16(af, bf, acc, 0, 0, 0); }
;         __syncthreads();
; #pragma unroll
;         for (int i = 0; i < 16; ++i) red[(wave * 16 + i) * 64 + lane] = acc[i];
;         __syncthreads();
; #pragma unroll
;         for (int h2 = 0; h2 < 2; ++h2) {
;             const int e = tid + h2 * 512, i = e >> 6, ln = e & 63;
;             float v = 0.f;
; #pragma unroll
;             for (int w = 0; w < 8; ++w) v += red[(w * 16 + i) * 64 + ln];
;             const int row = m0 + (i & 3) + 8 * (i >> 2) + 4 * (ln >> 5), col = n0 + (ln & 31);
;             if (MODE == 0) { O[(size_t)row * ldc + col] = (bf16_t)f2bf(v * rstd[row]); }
.LBB0_169:
	s_ashr_i32 s11, s10, 31
	s_lshr_b32 s11, s11, 26
	s_add_i32 s11, s10, s11
	s_ashr_i32 s11, s11, 6
	s_lshl_b32 s12, s11, 5
	s_lshl_b32 s11, s11, 11
	v_or_b32_e32 v0, s12, v20
	v_subrev_u32_e32 v48, s11, v26
	v_ashrrev_i32_e32 v1, 31, v0
	v_ashrrev_i32_e32 v49, 31, v48
	v_lshlrev_b64 v[0:1], 11, v[0:1]
	v_lshlrev_b64 v[2:3], 11, v[48:49]
	v_lshl_add_u64 v[50:51], v[16:17], 0, v[0:1]
	v_lshl_add_u64 v[52:53], v[18:19], 0, v[2:3]
	s_add_i32 s10, s10, s38
	v_add_u32_e32 v26, s8, v26
	s_cmpk_lt_i32 s10, 0x200
	v_or_b32_e32 v41, s12, v21
	v_or_b32_e32 v40, v41, v23
	v_add_u32_e32 v42, v41, v25
	v_ashrrev_i32_e32 v41, 31, v40
	v_ashrrev_i32_e32 v43, 31, v42
	v_lshl_add_u64 v[32:33], v[40:41], 2, s[6:7]
	v_lshl_add_u64 v[34:35], v[42:43], 2, s[6:7]
	global_load_dwordx4 v[100:103], v[50:51], off
	global_load_dwordx4 v[132:135], v[52:53], off
	global_load_dwordx4 v[104:107], v[50:51], off offset:32
	global_load_dwordx4 v[136:139], v[52:53], off offset:32
	global_load_dwordx4 v[108:111], v[50:51], off offset:64
	global_load_dwordx4 v[140:143], v[52:53], off offset:64
	global_load_dwordx4 v[112:115], v[50:51], off offset:96
	global_load_dwordx4 v[144:147], v[52:53], off offset:96
	global_load_dwordx4 v[116:119], v[50:51], off offset:128
	global_load_dwordx4 v[148:151], v[52:53], off offset:128
	global_load_dwordx4 v[120:123], v[50:51], off offset:160
	global_load_dwordx4 v[152:155], v[52:53], off offset:160
	global_load_dwordx4 v[124:127], v[50:51], off offset:192
	global_load_dwordx4 v[156:159], v[52:53], off offset:192
	global_load_dwordx4 v[128:131], v[50:51], off offset:224
	global_load_dwordx4 v[160:163], v[52:53], off offset:224
	s_waitcnt vmcnt(14)
	v_mfma_f32_32x32x16_bf16 v[0:15], v[100:103], v[132:135], 0
	s_waitcnt vmcnt(12)
	v_mfma_f32_32x32x16_bf16 v[0:15], v[104:107], v[136:139], v[0:15]
	s_waitcnt vmcnt(10)
	v_mfma_f32_32x32x16_bf16 v[0:15], v[108:111], v[140:143], v[0:15]
	s_waitcnt vmcnt(8)
	v_mfma_f32_32x32x16_bf16 v[0:15], v[112:115], v[144:147], v[0:15]
	s_waitcnt vmcnt(6)
	v_mfma_f32_32x32x16_bf16 v[0:15], v[116:119], v[148:151], v[0:15]
	s_waitcnt vmcnt(4)
	v_mfma_f32_32x32x16_bf16 v[0:15], v[120:123], v[152:155], v[0:15]
	s_barrier
	s_waitcnt vmcnt(2)
	v_mfma_f32_32x32x16_bf16 v[0:15], v[124:127], v[156:159], v[0:15]
	s_waitcnt vmcnt(0)
	v_mfma_f32_32x32x16_bf16 v[0:15], v[128:131], v[160:163], v[0:15]
	s_nop 11
	ds_write2st64_b32 v27, v0, v1 offset1:1
	ds_write2st64_b32 v27, v2, v3 offset0:2 offset1:3
	ds_write2st64_b32 v27, v4, v5 offset0:4 offset1:5
	ds_write2st64_b32 v27, v6, v7 offset0:6 offset1:7
	ds_write2st64_b32 v27, v8, v9 offset0:8 offset1:9
	ds_write2st64_b32 v27, v10, v11 offset0:10 offset1:11
	ds_write2st64_b32 v27, v12, v13 offset0:12 offset1:13
	ds_write2st64_b32 v27, v14, v15 offset0:14 offset1:15
	s_waitcnt lgkmcnt(0)
	s_barrier
	global_load_dword v32, v[32:33], off
	s_nop 0
	global_load_dword v33, v[34:35], off
	v_lshl_add_u64 v[0:1], v[48:49], 1, s[2:3]
	v_lshlrev_b64 v[2:3], 12, v[40:41]
	v_lshlrev_b64 v[4:5], 12, v[42:43]
	v_lshl_add_u64 v[2:3], v[0:1], 0, v[2:3]
	v_lshl_add_u64 v[0:1], v[0:1], 0, v[4:5]
	ds_read2st64_b32 v[4:5], v22 offset1:16
	ds_read2st64_b32 v[6:7], v22 offset0:32 offset1:48
	ds_read2st64_b32 v[8:9], v22 offset0:64 offset1:80
	ds_read2st64_b32 v[10:11], v22 offset0:96 offset1:112
	ds_read2st64_b32 v[12:13], v24 offset1:16
	ds_read2st64_b32 v[14:15], v24 offset0:32 offset1:48
	ds_read2st64_b32 v[28:29], v24 offset0:64 offset1:80
	ds_read2st64_b32 v[30:31], v24 offset0:96 offset1:112
	s_waitcnt lgkmcnt(7)
	v_add_f32_e32 v4, 0, v4
	s_waitcnt lgkmcnt(3)
	v_add_f32_e32 v12, 0, v12
	v_add_f32_e32 v4, v4, v5
	v_add_f32_e32 v5, v12, v13
	v_add_f32_e32 v4, v4, v6
	s_waitcnt lgkmcnt(2)
	v_add_f32_e32 v5, v5, v14
	v_add_f32_e32 v4, v4, v7
	v_add_f32_e32 v5, v5, v15
	v_add_f32_e32 v4, v4, v8
	s_waitcnt lgkmcnt(1)
	v_add_f32_e32 v5, v5, v28
	v_add_f32_e32 v4, v4, v9
	v_add_f32_e32 v5, v5, v29
	v_add_f32_e32 v4, v4, v10
	s_waitcnt lgkmcnt(0)
	v_add_f32_e32 v5, v5, v30
	v_add_f32_e32 v4, v4, v11
	v_add_f32_e32 v5, v5, v31
	s_waitcnt vmcnt(1)
	v_mul_f32_e32 v4, v4, v32
	s_waitcnt vmcnt(0)
	v_mul_f32_e32 v5, v5, v33
	v_bfe_u32 v6, v4, 16, 1
	v_bfe_u32 v7, v5, 16, 1
	v_add3_u32 v4, v4, v6, s9
	v_add3_u32 v5, v5, v7, s9
	global_store_short_d16_hi v[2:3], v4, off
	global_store_short_d16_hi v[0:1], v5, off
	s_cbranch_scc1 .LBB0_169

; __device__ __forceinline__ unsigned f2bf(float f) { unsigned u = __float_as_uint(f); return (u + 0x7fffu + ((u >> 16) & 1u)) >> 16; }
; template <int MODE>
; __device__ __forceinline__ void mini_gemm(LAS unsigned char* lds, const bf16_t* A, const bf16_t* Bt, int K, int N, bf16_t* O, int ldc, const float* rstd, float* sumsq, int bx, int G, int tid, int wave, int lane) {
;     ...
;     for (int tile = bx; tile < ntiles; tile += G) {
;         const int m0 = (tile / ntn) * 32, n0 = (tile % ntn) * 32;
;         const bf16_t* ap = A + (size_t)(m0 + r) * K + wave * kw + 8 * hf; const bf16_t* bp = Bt + (size_t)(n0 + r) * K + wave * kw + 8 * hf;
;         f32x16 acc; for (int i = 0; i < 16; ++i) acc[i] = 0.f;
;         for (int k = 0; k < kw; k += 16) { const bf16x8 af = *(const bf16x8*)(ap + k), bf = *(const bf16x8*)(bp + k); acc = __builtin_amdgcn_mfma_f32_32x32x16_bf16(af, bf, acc, 0, 0, 0); }
;         __syncthreads();
; #pragma unroll
;         for (int i = 0; i < 16; ++i) red[(wave * 16 + i) * 64 + lane] = acc[i];
;         __syncthreads();
; #pragma unroll
;         for (int h2 = 0; h2 < 2; ++h2) {
;             const int e = tid + h2 * 512, i = e >> 6, ln = e & 63;
;             float v = 0.f;
; #pragma unroll
;             for (int w = 0; w < 8; ++w) v += red[(w * 16 + i) * 64 + ln];
;             const int row = m0 + (i & 3) + 8 * (i >> 2) + 4 * (ln >> 5), col = n0 + (ln & 31);
;             if (MODE == 0) { O[(size_t)row * ldc + col] = (bf16_t)f2bf(v * rstd[row]); }
;             else { O[(size_t)row * ldc + col] = (bf16_t)f2bf(v); float ss = v * v;
; #pragma unroll
;                 for (int o = 1; o < 32; o <<= 1) ss += __shfl_xor(ss, o);
;                 if ((ln & 31) == 0) atomicAdd(sumsq + row, ss); }
.LBB0_990:
	s_ashr_i32 s0, s10, 31
	s_lshr_b32 s0, s0, 27
	s_add_i32 s0, s10, s0
	s_and_b32 s1, s0, 0xffffffe0
	v_or_b32_e32 v0, s1, v20
	v_ashrrev_i32_e32 v1, 31, v0
	v_lshlrev_b64 v[0:1], 11, v[0:1]
	v_lshl_add_u64 v[56:57], v[16:17], 0, v[0:1]
	s_lshl_b32 s0, s0, 5
	s_and_b32 s0, s0, 0xfffffc00
	v_subrev_u32_e32 v54, s0, v31
	v_ashrrev_i32_e32 v55, 31, v54
	s_waitcnt lgkmcnt(0)
	v_lshlrev_b64 v[4:5], 11, v[54:55]
	v_lshl_add_u64 v[58:59], v[18:19], 0, v[4:5]
	global_load_dwordx4 v[100:103], v[56:57], off
	global_load_dwordx4 v[132:135], v[58:59], off
	global_load_dwordx4 v[104:107], v[56:57], off offset:32
	global_load_dwordx4 v[136:139], v[58:59], off offset:32
	global_load_dwordx4 v[108:111], v[56:57], off offset:64
	global_load_dwordx4 v[140:143], v[58:59], off offset:64
	global_load_dwordx4 v[112:115], v[56:57], off offset:96
	global_load_dwordx4 v[144:147], v[58:59], off offset:96
	global_load_dwordx4 v[116:119], v[56:57], off offset:128
	global_load_dwordx4 v[148:151], v[58:59], off offset:128
	global_load_dwordx4 v[120:123], v[56:57], off offset:160
	global_load_dwordx4 v[152:155], v[58:59], off offset:160
	global_load_dwordx4 v[124:127], v[56:57], off offset:192
	global_load_dwordx4 v[156:159], v[58:59], off offset:192
	global_load_dwordx4 v[128:131], v[56:57], off offset:224
	global_load_dwordx4 v[160:163], v[58:59], off offset:224
	s_waitcnt vmcnt(14)
	v_mfma_f32_32x32x16_bf16 v[0:15], v[100:103], v[132:135], 0
	s_waitcnt vmcnt(12)
	v_mfma_f32_32x32x16_bf16 v[0:15], v[104:107], v[136:139], v[0:15]
	s_waitcnt vmcnt(10)
	v_mfma_f32_32x32x16_bf16 v[0:15], v[108:111], v[140:143], v[0:15]
	s_waitcnt vmcnt(8)
	v_mfma_f32_32x32x16_bf16 v[0:15], v[112:115], v[144:147], v[0:15]
	s_waitcnt vmcnt(6)
	v_mfma_f32_32x32x16_bf16 v[0:15], v[116:119], v[148:151], v[0:15]
	s_waitcnt vmcnt(4)
	v_mfma_f32_32x32x16_bf16 v[0:15], v[120:123], v[152:155], v[0:15]
	s_barrier
	s_waitcnt vmcnt(2)
	v_mfma_f32_32x32x16_bf16 v[0:15], v[124:127], v[156:159], v[0:15]
	s_waitcnt vmcnt(0)
	v_mfma_f32_32x32x16_bf16 v[0:15], v[128:131], v[160:163], v[0:15]
	s_nop 11
	ds_write2st64_b32 v32, v0, v1 offset1:1
	ds_write2st64_b32 v32, v2, v3 offset0:2 offset1:3
	ds_write2st64_b32 v32, v4, v5 offset0:4 offset1:5
	ds_write2st64_b32 v32, v6, v7 offset0:6 offset1:7
	ds_write2st64_b32 v32, v8, v9 offset0:8 offset1:9
	ds_write2st64_b32 v32, v10, v11 offset0:10 offset1:11
	ds_write2st64_b32 v32, v12, v13 offset0:12 offset1:13
	ds_write2st64_b32 v32, v14, v15 offset0:14 offset1:15
	s_waitcnt lgkmcnt(0)
	s_barrier
	ds_read2st64_b32 v[0:1], v22 offset1:16
	ds_read2st64_b32 v[2:3], v22 offset0:32 offset1:48
	ds_read2st64_b32 v[4:5], v22 offset0:64 offset1:80
	s_waitcnt lgkmcnt(2)
	v_add_f32_e32 v0, 0, v0
	v_add_f32_e32 v6, v0, v1
	ds_read2st64_b32 v[0:1], v22 offset0:96 offset1:112
	s_waitcnt lgkmcnt(2)
	v_add_f32_e32 v2, v6, v2
	v_add_f32_e32 v2, v2, v3
	s_waitcnt lgkmcnt(1)
	v_add_f32_e32 v2, v2, v4
	v_add_f32_e32 v2, v2, v5
	s_waitcnt lgkmcnt(0)
	v_add_f32_e32 v0, v2, v0
	v_add_f32_e32 v3, v0, v1
	v_mul_f32_e32 v0, v3, v3
	ds_bpermute_b32 v0, v24, v0
	v_or_b32_e32 v4, s1, v21
	v_or_b32_e32 v2, v4, v23
	v_bfe_u32 v7, v3, 16, 1
	v_add3_u32 v7, v3, v7, s9
	s_waitcnt lgkmcnt(0)
	v_fmac_f32_e32 v0, v3, v3
	ds_bpermute_b32 v1, v25, v0
	v_ashrrev_i32_e32 v3, 31, v2
	v_lshlrev_b64 v[8:9], 11, v[2:3]
	s_waitcnt lgkmcnt(0)
	v_add_f32_e32 v0, v0, v1
	ds_bpermute_b32 v1, v26, v0
	s_waitcnt lgkmcnt(0)
	v_add_f32_e32 v5, v0, v1
	ds_bpermute_b32 v6, v27, v5
	v_lshl_add_u64 v[0:1], v[54:55], 1, s[2:3]
	v_lshl_add_u64 v[8:9], v[0:1], 0, v[8:9]
	global_store_short_d16_hi v[8:9], v7, off
	s_waitcnt lgkmcnt(0)
	v_add_f32_e32 v5, v5, v6
	ds_bpermute_b32 v6, v28, v5
	s_and_saveexec_b64 s[0:1], vcc
	s_cbranch_execz .LBB0_992
	v_lshl_add_u64 v[2:3], v[2:3], 2, s[6:7]
	s_waitcnt lgkmcnt(0)
	v_add_f32_e32 v5, v5, v6
	global_atomic_add_f32 v[2:3], v5, off
